# MLA role split with one static priority raise for the vector-first wave half (s_setprio 2 vs 1); hot loops page-contained
# baseline (speedup 1.0000x reference)
; template <int GRP> ...
;     ...
;     if (wid >= 4) __builtin_amdgcn_s_setprio(1);
;     asm volatile("s_nop 15\n\ts_nop 7" : "+v"(pa0), "+v"(pa1));
;     for (int s = 0; s < NSTEP - 2; s += 2) { att_step<GRP, true>(C, S, s, pa0, pa1, pb0, pb1, kA, pA, vA); att_step<GRP, true>(C, S, s + 1, pb0, pb1, pa0, pa1, kA, pA, vA); }
.Lmla_T_entry:
	s_setprio 2
	s_branch .Lpagefit_3
	s_nop 0
	s_nop 0
	s_nop 0
	s_nop 0
	s_nop 0
	s_nop 0
	s_nop 0
	s_nop 0
	s_nop 0
	s_nop 0
	s_nop 0
	s_nop 0
	s_nop 0
	s_nop 0
	s_nop 0
	s_nop 0
	s_nop 0
	s_nop 0
	s_nop 0
	s_nop 0
	s_nop 0
	s_nop 0
	s_nop 0
	s_nop 0
	s_nop 0
	s_nop 0
	s_nop 0
	s_nop 0
	s_nop 0
	s_nop 0
	s_nop 0
	s_nop 0
	s_nop 0
	s_nop 0
	s_nop 0
	s_nop 0
	s_nop 0
	s_nop 0
	s_nop 0
	s_nop 0
	s_nop 0
	s_nop 0
	s_nop 0
	s_nop 0
	s_nop 0
	s_nop 0
	s_nop 0
	s_nop 0
	s_nop 0
	s_nop 0
	s_nop 0
	s_nop 0
	s_nop 0
	s_nop 0
	s_nop 0
	s_nop 0
	s_nop 0
	s_nop 0
	s_nop 0
	s_nop 0
	s_nop 0
	s_nop 0
	s_nop 0
	s_nop 0
	s_nop 0
	s_nop 0
	s_nop 0
	s_nop 0
	s_nop 0
	s_nop 0
	s_nop 0
	s_nop 0
	s_nop 0
	s_nop 0
	s_nop 0
	s_nop 0
	s_nop 0
	s_nop 0
	s_nop 0
	s_nop 0
	s_nop 0
	s_nop 0
	s_nop 0
	s_nop 0
	s_nop 0
	s_nop 0
	s_nop 0
	s_nop 0
	s_nop 0
	s_nop 0
	s_nop 0
	s_nop 0
	s_nop 0
	s_nop 0
	s_nop 0
	s_nop 0
	s_nop 0
	s_nop 0
	s_nop 0
	s_nop 0
	s_nop 0
	s_nop 0
	s_nop 0
	s_nop 0
	s_nop 0
	s_nop 0
	s_nop 0
	s_nop 0
	s_nop 0
	s_nop 0
	s_nop 0
	s_nop 0
	s_nop 0
	s_nop 0
	s_nop 0
	s_nop 0
	s_nop 0
	s_nop 0
	s_nop 0
	s_nop 0
	s_nop 0
	s_nop 0
	s_nop 0
	s_nop 0
	s_nop 0
	s_nop 0
	s_nop 0
	s_nop 0
	s_nop 0
	s_nop 0
	s_nop 0
	s_nop 0
	s_nop 0
	s_nop 0
	s_nop 0
	s_nop 0
	s_nop 0
	s_nop 0
	s_nop 0
	s_nop 0
	s_nop 0
	s_nop 0
	s_nop 0
	s_nop 0
	s_nop 0
	s_nop 0
	s_nop 0
	s_nop 0
	s_nop 0
	s_nop 0
	s_nop 0
	s_nop 0
	s_nop 0
	s_nop 0
	s_nop 0
	s_nop 0
	s_nop 0
	s_nop 0
	s_nop 0
	s_nop 0
	s_nop 0
	s_nop 0
	s_nop 0
	s_nop 0
	s_nop 0
	s_nop 0
	s_nop 0
	s_nop 0
	s_nop 0
	s_nop 0
	s_nop 0
	s_nop 0
	s_nop 0
	s_nop 0
	s_nop 0
	s_nop 0
	s_nop 0
	s_nop 0
	s_nop 0
	s_nop 0
	s_nop 0
	s_nop 0
	s_nop 0
	s_nop 0
	s_nop 0
	s_nop 0
	s_nop 0
	s_nop 0
	s_nop 0
	s_nop 0
	s_nop 0
	s_nop 0
	s_nop 0
	s_nop 0
	s_nop 0
	s_nop 0
	s_nop 0
	s_nop 0
	s_nop 0
	s_nop 0
	s_nop 0
	s_nop 0
	s_nop 0
	s_nop 0
	s_nop 0
	s_nop 0
	s_nop 0
	s_nop 0
	s_nop 0
	s_nop 0
	s_nop 0
	s_nop 0
	s_nop 0
	s_nop 0
	s_nop 0
	s_nop 0
	s_nop 0
	s_nop 0
	s_nop 0
	s_nop 0
	s_nop 0
	s_nop 0
	s_nop 0
	s_nop 0
	s_nop 0
	s_nop 0
	s_nop 0
	s_nop 0
	s_nop 0
	s_nop 0
	s_nop 0
	s_nop 0
	s_nop 0
	s_nop 0
	s_nop 0
	s_nop 0
	s_nop 0
	s_nop 0
	s_nop 0
	s_nop 0
	s_nop 0
	s_nop 0
	s_nop 0
	s_nop 0
	s_nop 0
	s_nop 0
	s_nop 0
	s_nop 0
	s_nop 0
	s_nop 0
	s_nop 0
	s_nop 0
	s_nop 0
	s_nop 0
	s_nop 0
	s_nop 0
	s_nop 0
	s_nop 0
	s_nop 0
	s_nop 0
	s_nop 0
	s_nop 0
	s_nop 0
	s_nop 0
	s_nop 0
	s_nop 0
	s_nop 0
	s_nop 0
	s_nop 0
	s_nop 0
	s_nop 0
	s_nop 0
	s_nop 0
	s_nop 0
	s_nop 0
	s_nop 0
	s_nop 0
	s_nop 0
	s_nop 0
	s_nop 0
	s_nop 0
	s_nop 0
	s_nop 0
	s_nop 0
	s_nop 0
	s_nop 0
	s_nop 0
	s_nop 0
	s_nop 0
	s_nop 0
	s_nop 0
	s_nop 0
	s_nop 0
	s_nop 0
	s_nop 0
	s_nop 0
	s_nop 0
	s_nop 0
	s_nop 0
	s_nop 0
	s_nop 0
	s_nop 0
	s_nop 0
	s_nop 0
	s_nop 0
	s_nop 0
	s_nop 0
	s_nop 0
	s_nop 0
	s_nop 0
	s_nop 0
	s_nop 0
	s_nop 0
	s_nop 0
	s_nop 0
	s_nop 0
	s_nop 0
	s_nop 0
	s_nop 0
	s_nop 0
	s_nop 0
	s_nop 0
	s_nop 0
	s_nop 0
	s_nop 0
	s_nop 0
	s_nop 0
	s_nop 0
	s_nop 0
	s_nop 0
	s_nop 0
	s_nop 0
	s_nop 0
	s_nop 0
	s_nop 0
	s_nop 0
	s_nop 0
	s_nop 0
	s_nop 0
	s_nop 0
	s_nop 0
	s_nop 0
	s_nop 0
	s_nop 0
	s_nop 0
	s_nop 0
	s_nop 0
	s_nop 0
	s_nop 0
	s_nop 0
	s_nop 0
	s_nop 0
	s_nop 0
	s_nop 0
	s_nop 0
	s_nop 0
	s_nop 0
	s_nop 0
	s_nop 0
	s_nop 0
	s_nop 0
	s_nop 0
	s_nop 0
	s_nop 0
	s_nop 0
	s_nop 0
	s_nop 0
	s_nop 0
	s_nop 0
	s_nop 0
	s_nop 0
	s_nop 0
	s_nop 0
	s_nop 0
	s_nop 0
	s_nop 0
	s_nop 0
	s_nop 0
	s_nop 0
	s_nop 0
	s_nop 0
	s_nop 0
	s_nop 0
	s_nop 0
	s_nop 0
	s_nop 0
	s_nop 0
	s_nop 0
	s_nop 0
	s_nop 0
	s_nop 0
	s_nop 0
	s_nop 0
	s_nop 0
	s_nop 0
	s_nop 0
	s_nop 0
	s_nop 0
	s_nop 0
	s_nop 0
	s_nop 0
	s_nop 0
	s_nop 0
	s_nop 0
	s_nop 0
	s_nop 0
	s_nop 0
	s_nop 0
	s_nop 0
	s_nop 0
	s_nop 0
	s_nop 0
	s_nop 0
	s_nop 0
	s_nop 0
	s_nop 0
	s_nop 0
	s_nop 0
	s_nop 0
	s_nop 0
	s_nop 0
	s_nop 0
	s_nop 0
	s_nop 0
	s_nop 0
	s_nop 0
	s_nop 0
	s_nop 0
	s_nop 0
	s_nop 0
	s_nop 0
	s_nop 0
	s_nop 0
	s_nop 0
	s_nop 0
	s_nop 0
	s_nop 0
	s_nop 0
	s_nop 0
	s_nop 0
	s_nop 0
	s_nop 0
	s_nop 0
	s_nop 0
	s_nop 0
	s_nop 0
	s_nop 0
	s_nop 0
	s_nop 0
	s_nop 0
	s_nop 0
	s_nop 0
	s_nop 0
	s_nop 0
	s_nop 0
	s_nop 0
	s_nop 0
	s_nop 0
	s_nop 0
	s_nop 0
	s_nop 0
	s_nop 0
	s_nop 0
	s_nop 0
	s_nop 0
	s_nop 0
	s_nop 0
	s_nop 0
	s_nop 0
	s_nop 0
	s_nop 0
	s_nop 0
	s_nop 0
	s_nop 0
	s_nop 0
	s_nop 0
	s_nop 0
	s_nop 0
	s_nop 0
	s_nop 0
	s_nop 0
	s_nop 0
	s_nop 0
	s_nop 0
	s_nop 0
	s_nop 0
	s_nop 0
	s_nop 0
	s_nop 0
	s_nop 0
	s_nop 0
	s_nop 0
	s_nop 0
	s_nop 0
	s_nop 0
	s_nop 0
	s_nop 0
	s_nop 0
	s_nop 0
	s_nop 0
	s_nop 0
	s_nop 0
	s_nop 0
	s_nop 0
	s_nop 0
	s_nop 0
	s_nop 0
	s_nop 0
	s_nop 0
	s_nop 0
	s_nop 0
	s_nop 0
	s_nop 0
	s_nop 0
	s_nop 0
	s_nop 0
	s_nop 0
	s_nop 0
	s_nop 0
	s_nop 0
	s_nop 0
	s_nop 0
	s_nop 0
	s_nop 0
	s_nop 0
	s_nop 0
	s_nop 0
	s_nop 0
	s_nop 0
	s_nop 0
	s_nop 0
	s_nop 0
	s_nop 0
	s_nop 0
	s_nop 0
	s_nop 0
	s_nop 0
	s_nop 0
	s_nop 0
	s_nop 0
	s_nop 0
	s_nop 0
	s_nop 0
	s_nop 0
	s_nop 0
	s_nop 0
	s_nop 0
	s_nop 0
	s_nop 0
	s_nop 0
	s_nop 0
	s_nop 0
	s_nop 0
	s_nop 0
	s_nop 0
	s_nop 0
	s_nop 0
	s_nop 0
	s_nop 0
	s_nop 0
	s_nop 0
	s_nop 0
	s_nop 0
	s_nop 0
	s_nop 0
	s_nop 0
	s_nop 0
	s_nop 0
	s_nop 0
	s_nop 0
	s_nop 0
	s_nop 0
	s_nop 0
	s_nop 0
	s_nop 0
	s_nop 0
	s_nop 0
	s_nop 0
	s_nop 0
	s_nop 0
	s_nop 0
	s_nop 0
	s_nop 0
	s_nop 0
	s_nop 0
	s_nop 0
	s_nop 0
	s_nop 0
	s_nop 0
	s_nop 0
	s_nop 0
	s_nop 0
	s_nop 0
	s_nop 0
	s_nop 0
	s_nop 0
	s_nop 0
	s_nop 0
	s_nop 0
	s_nop 0
	s_nop 0
	s_nop 0
	s_nop 0
	s_nop 0
	s_nop 0
	s_nop 0
	s_nop 0
	s_nop 0
	s_nop 0
	s_nop 0
	s_nop 0
	s_nop 0
	s_nop 0
	s_nop 0
	s_nop 0
	s_nop 0
	s_nop 0
	s_nop 0
	s_nop 0
	s_nop 0
	s_nop 0
	s_nop 0
	s_nop 0
	s_nop 0
	s_nop 0
	s_nop 0
	s_nop 0
	s_nop 0
	s_nop 0
	s_nop 0
	s_nop 0
	s_nop 0
	s_nop 0
	s_nop 0
	s_nop 0
	s_nop 0
	s_nop 0
	s_nop 0
	s_nop 0
	s_nop 0
	s_nop 0
	s_nop 0
	s_nop 0
	s_nop 0
	s_nop 0
	s_nop 0
	s_nop 0
	s_nop 0
	s_nop 0
	s_nop 0
